# compressed branch pass 1: far blocks (prefix of the block loop) run by a hand-written loop (packed math, in-place K prefetch, no accumulator copies); compiler loop continues with the near blocks
# speedup vs baseline: 1.0200x; 1.0040x over previous
.LBB0_1278:
	v_mov_b32_e32 v4, v66
	s_nop 1
	v_permlane32_swap_b32_e32 v66, v4
	s_add_u32 s4, s8, s38
	v_add_f32_e32 v4, v66, v4
	s_addc_u32 s5, s9, s39
	s_waitcnt vmcnt(16)
	v_div_scale_f32 v5, s[8:9], v4, v4, v1
	v_rcp_f32_e32 v6, v5
	v_ashrrev_i32_e32 v211, 31, v210
	v_lshlrev_b64 v[2:3], 7, v[210:211]
	v_lshl_add_u64 v[10:11], s[4:5], 0, v[2:3]
	v_fma_f32 v2, -v5, v6, 1.0
	v_fmac_f32_e32 v6, v2, v6
	v_div_scale_f32 v2, vcc, v1, v4, v1
	v_mul_f32_e32 v3, v2, v6
	v_fma_f32 v7, -v5, v3, v2
	v_fmac_f32_e32 v3, v7, v6
	v_fma_f32 v2, -v5, v3, v2
	v_div_fmas_f32 v2, v2, v6, v3
	v_div_fixup_f32 v1, v2, v4, v1
	v_cmp_lt_f32_e32 vcc, 0, v4
	s_waitcnt vmcnt(1)
	v_lshl_add_u64 v[178:179], v[10:11], 0, s[36:37]
	s_mov_b64 s[4:5], s[0:1]
	v_cndmask_b32_e32 v12, 0, v1, vcc
	v_pk_mul_f32 v[4:5], v[50:51], v[12:13] op_sel_hi:[1,0]
	v_pk_mul_f32 v[2:3], v[34:35], v[12:13] op_sel_hi:[1,0]
	v_cvt_pk_bf16_f32 v6, v4, v5
	v_pk_mul_f32 v[4:5], v[36:37], v[12:13] op_sel_hi:[1,0]
	v_cvt_pk_bf16_f32 v2, v2, v3
	v_cvt_pk_bf16_f32 v3, v4, v5
	v_pk_mul_f32 v[4:5], v[52:53], v[12:13] op_sel_hi:[1,0]
	v_pk_mul_f32 v[14:15], v[40:41], v[12:13] op_sel_hi:[1,0]
	v_cvt_pk_bf16_f32 v7, v4, v5
	v_pk_mul_f32 v[4:5], v[38:39], v[12:13] op_sel_hi:[1,0]
	v_add_co_u32_e32 v10, vcc, s77, v10
	v_cvt_pk_bf16_f32 v4, v4, v5
	v_pk_mul_f32 v[8:9], v[54:55], v[12:13] op_sel_hi:[1,0]
	v_cvt_pk_bf16_f32 v5, v14, v15
	v_pk_mul_f32 v[14:15], v[56:57], v[12:13] op_sel_hi:[1,0]
	v_addc_co_u32_e32 v11, vcc, 0, v11, vcc
	v_cvt_pk_bf16_f32 v8, v8, v9
	v_cvt_pk_bf16_f32 v9, v14, v15
	global_store_dwordx4 v[10:11], v[2:5], off
	global_store_dwordx4 v[178:179], v[6:9], off offset:32
	v_pk_mul_f32 v[10:11], v[48:49], v[12:13] op_sel_hi:[1,0]
	v_pk_mul_f32 v[4:5], v[58:59], v[12:13] op_sel_hi:[1,0]
	v_pk_mul_f32 v[2:3], v[42:43], v[12:13] op_sel_hi:[1,0]
	v_cvt_pk_bf16_f32 v6, v4, v5
	v_pk_mul_f32 v[4:5], v[44:45], v[12:13] op_sel_hi:[1,0]
	v_cvt_pk_bf16_f32 v2, v2, v3
	v_cvt_pk_bf16_f32 v3, v4, v5
	v_pk_mul_f32 v[4:5], v[60:61], v[12:13] op_sel_hi:[1,0]
	v_pk_mul_f32 v[8:9], v[62:63], v[12:13] op_sel_hi:[1,0]
	v_cvt_pk_bf16_f32 v7, v4, v5
	v_pk_mul_f32 v[4:5], v[46:47], v[12:13] op_sel_hi:[1,0]
	v_cvt_pk_bf16_f32 v8, v8, v9
	v_cvt_pk_bf16_f32 v4, v4, v5
	v_cvt_pk_bf16_f32 v5, v10, v11
	v_pk_mul_f32 v[10:11], v[64:65], v[12:13] op_sel_hi:[1,0]
	s_mov_b32 s45, s27
	v_cvt_pk_bf16_f32 v9, v10, v11
	global_store_dwordx4 v[178:179], v[2:5], off offset:16
	global_store_dwordx4 v[178:179], v[6:9], off offset:48
	s_load_dwordx2 s[4:5], s[4:5], 0xb0
	s_lshl_b64 s[8:9], s[44:45], 9
	s_lshl_b32 s10, s44, 2
	s_add_u32 s8, s8, 0x2100
	s_add_i32 s15, s10, 0xffffffb9
	v_lshlrev_b32_e32 v1, 1, v229
	s_and_b32 s16, s8, 0xffffe000
	s_add_i32 s14, s14, s90
	v_and_b32_e32 v2, 0x70, v1
	s_waitcnt lgkmcnt(0)
	s_add_u32 s4, s4, s40
	v_mov_b32_e32 v16, v195
	v_mov_b32_e32 v17, v195
	v_and_b32_e32 v130, 64, v1
	v_or_b32_e32 v131, 48, v2
	s_waitcnt vmcnt(4)
	v_or_b32_e32 v135, 0xb0, v2
	v_or_b32_e32 v139, 0x130, v2
	v_or_b32_e32 v143, 0x1b0, v2
	v_or_b32_e32 v147, 0x230, v2
	v_or_b32_e32 v151, 0x2b0, v2
	v_or_b32_e32 v155, 0x330, v2
	v_or_b32_e32 v159, 0x3b0, v2
	v_add_u32_e32 v161, s14, v228
	s_addc_u32 s5, s5, s41
	v_mov_b32_e32 v2, v195
	v_mov_b32_e32 v3, v195
	v_mov_b32_e32 v4, v195
	v_mov_b32_e32 v5, v195
	v_mov_b32_e32 v6, v195
	v_mov_b32_e32 v7, v195
	v_mov_b32_e32 v8, v195
	v_mov_b32_e32 v9, v195
	v_mov_b32_e32 v10, v195
	v_mov_b32_e32 v11, v195
	v_mov_b32_e32 v12, v195
	v_mov_b32_e32 v13, v195
	v_mov_b32_e32 v14, v195
	v_mov_b32_e32 v15, v195
	v_mov_b64_e32 v[32:33], v[16:17]
	v_lshl_add_u32 v180, v227, 9, s92
	s_mov_b32 s11, 0
	v_or_b32_e32 v1, 16, v130
	v_or_b32_e32 v132, 32, v130
	v_or_b32_e32 v133, 0x90, v130
	v_or_b32_e32 v134, 0x80, v130
	v_or_b32_e32 v136, 0xa0, v130
	v_or_b32_e32 v137, 0x110, v130
	v_or_b32_e32 v138, 0x100, v130
	v_or_b32_e32 v140, 0x120, v130
	v_or_b32_e32 v141, 0x190, v130
	v_or_b32_e32 v142, 0x180, v130
	v_or_b32_e32 v144, 0x1a0, v130
	v_or_b32_e32 v145, 0x210, v130
	v_or_b32_e32 v146, 0x200, v130
	v_or_b32_e32 v148, 0x220, v130
	v_or_b32_e32 v149, 0x290, v130
	v_or_b32_e32 v150, 0x280, v130
	v_or_b32_e32 v152, 0x2a0, v130
	v_or_b32_e32 v153, 0x310, v130
	v_or_b32_e32 v154, 0x300, v130
	v_or_b32_e32 v156, 0x320, v130
	v_or_b32_e32 v157, 0x390, v130
	v_or_b32_e32 v158, 0x380, v130
	v_or_b32_e32 v160, 0x3a0, v130
	v_lshl_add_u64 v[162:163], s[4:5], 0, v[194:195]
	v_mov_b32_e32 v165, 0
	v_mov_b32_e32 v166, 0xff800000
	s_mov_b64 s[12:13], 0
	v_mov_b32_e32 v164, v161
	v_mov_b64_e32 v[30:31], v[14:15]
	v_mov_b64_e32 v[28:29], v[12:13]
	v_mov_b64_e32 v[26:27], v[10:11]
	v_mov_b64_e32 v[24:25], v[8:9]
	v_mov_b64_e32 v[22:23], v[6:7]
	v_mov_b64_e32 v[20:21], v[4:5]
	v_mov_b64_e32 v[18:19], v[2:3]
	s_cmp_lt_i32 s11, s15
	s_cbranch_scc0 .LBB0_1279
	v_readfirstlane_b32 s18, v162
	v_readfirstlane_b32 s19, v163
	s_add_u32 s18, s18, 0x7e00000
	s_addc_u32 s19, s19, 0
	global_load_dwordx4 v[66:69], v194, s[18:19]
	global_load_dwordx4 v[70:73], v194, s[18:19] offset:1024
	global_load_dwordx4 v[74:77], v194, s[18:19] offset:2048
	global_load_dwordx4 v[78:81], v194, s[18:19] offset:3072
	global_load_dwordx4 v[82:85], v200, s[18:19]
	global_load_dwordx4 v[86:89], v202, s[18:19]
	global_load_dwordx4 v[90:93], v204, s[18:19]
	global_load_dwordx4 v[94:97], v206, s[18:19]
	ds_read_b128 v[234:237], v224
	ds_read_b128 v[238:241], v224 offset:32
	ds_read_b128 v[242:245], v224 offset:64
	ds_read_b128 v[246:249], v224 offset:96
	v_mov_b32_e32 v190, 0x3fb8aa3b
	s_waitcnt lgkmcnt(0)
.Lc1_loop:
	s_add_u32 s20, s18, 0x80000
	s_addc_u32 s21, s19, 0
	global_load_dwordx4 v[98:101], v194, s[20:21]
	global_load_dwordx4 v[114:117], v200, s[20:21]
	global_load_dwordx4 v[102:105], v194, s[20:21] offset:1024
	global_load_dwordx4 v[118:121], v202, s[20:21]
	global_load_dwordx4 v[106:109], v194, s[20:21] offset:2048
	global_load_dwordx4 v[122:125], v204, s[20:21]
	global_load_dwordx4 v[110:113], v194, s[20:21] offset:3072
	global_load_dwordx4 v[126:129], v206, s[20:21]
	s_add_i32 s4, s11, 64
	s_cmp_lt_i32 s4, s15
	s_cselect_b32 s4, 1, 0
	s_add_u32 s5, s12, 0x2000
	s_cmp_lg_u32 s5, s16
	s_cselect_b32 s5, 1, 0
	s_and_b32 s24, s4, s5
	s_waitcnt vmcnt(8)
	v_mfma_f32_32x32x16_bf16 v[34:49], v[66:69], v[234:237], 0
	v_mfma_f32_32x32x16_bf16 v[50:65], v[82:85], v[234:237], 0
	v_mfma_f32_32x32x16_bf16 v[34:49], v[70:73], v[238:241], v[34:49]
	v_mfma_f32_32x32x16_bf16 v[50:65], v[86:89], v[238:241], v[50:65]
	v_mfma_f32_32x32x16_bf16 v[34:49], v[74:77], v[242:245], v[34:49]
	v_mfma_f32_32x32x16_bf16 v[50:65], v[90:93], v[242:245], v[50:65]
	v_mfma_f32_32x32x16_bf16 v[34:49], v[78:81], v[246:249], v[34:49]
	v_mfma_f32_32x32x16_bf16 v[50:65], v[94:97], v[246:249], v[50:65]
	s_cmp_lg_u32 s24, 0
	s_cbranch_scc0 .Lc1_nok
	s_add_u32 s22, s18, 0x2000
	s_addc_u32 s23, s19, 0
	global_load_dwordx4 v[66:69], v194, s[22:23]
	global_load_dwordx4 v[70:73], v194, s[22:23] offset:1024
	global_load_dwordx4 v[74:77], v194, s[22:23] offset:2048
	global_load_dwordx4 v[78:81], v194, s[22:23] offset:3072
	global_load_dwordx4 v[82:85], v200, s[22:23]
	global_load_dwordx4 v[86:89], v202, s[22:23]
	global_load_dwordx4 v[90:93], v204, s[22:23]
	global_load_dwordx4 v[94:97], v206, s[22:23]
	s_branch .Lc1_k
.Lc1_nok:
	s_nop 7
	s_nop 3
.Lc1_k:
	s_nop 1
	v_max3_f32 v176, v34, v35, v36
	v_max3_f32 v176, v176, v37, v38
	v_max3_f32 v176, v176, v39, v40
	v_max3_f32 v176, v176, v41, v42
	v_max3_f32 v176, v176, v43, v44
	v_max3_f32 v176, v176, v45, v46
	v_max3_f32 v176, v176, v47, v48
	v_max3_f32 v176, v176, v49, v49
	v_max3_f32 v186, v50, v51, v52
	v_max3_f32 v186, v186, v53, v54
	v_max3_f32 v186, v186, v55, v56
	v_max3_f32 v186, v186, v57, v58
	v_max3_f32 v186, v186, v59, v60
	v_max3_f32 v186, v186, v61, v62
	v_max3_f32 v186, v186, v63, v64
	v_max3_f32 v186, v186, v65, v65
	v_max_f32_e32 v176, v176, v186
	v_fmamk_f32 v176, v176, 0x3fb8aa3b, v208
	v_mov_b32_e32 v177, v176
	s_nop 1
	v_permlane32_swap_b32_e32 v176, v177
	v_max3_f32 v186, v166, v176, v177
	v_cmp_neq_f32_e32 vcc, s68, v186
	s_nop 1
	v_cndmask_b32_e32 v182, 0, v186, vcc
	v_cmp_neq_f32_e32 vcc, v186, v166
	s_cbranch_vccz .Lc1_nr
	v_sub_f32_e32 v188, v166, v182
	v_exp_f32_e32 v188, v188
	s_nop 0
	v_pk_mul_f32 v[2:3], v[2:3], v[188:189] op_sel_hi:[1,0]
	v_pk_mul_f32 v[4:5], v[4:5], v[188:189] op_sel_hi:[1,0]
	v_pk_mul_f32 v[6:7], v[6:7], v[188:189] op_sel_hi:[1,0]
	v_pk_mul_f32 v[8:9], v[8:9], v[188:189] op_sel_hi:[1,0]
	v_pk_mul_f32 v[10:11], v[10:11], v[188:189] op_sel_hi:[1,0]
	v_pk_mul_f32 v[12:13], v[12:13], v[188:189] op_sel_hi:[1,0]
	v_pk_mul_f32 v[14:15], v[14:15], v[188:189] op_sel_hi:[1,0]
	v_pk_mul_f32 v[16:17], v[16:17], v[188:189] op_sel_hi:[1,0]
	v_pk_mul_f32 v[18:19], v[18:19], v[188:189] op_sel_hi:[1,0]
	v_pk_mul_f32 v[20:21], v[20:21], v[188:189] op_sel_hi:[1,0]
	v_pk_mul_f32 v[22:23], v[22:23], v[188:189] op_sel_hi:[1,0]
	v_pk_mul_f32 v[24:25], v[24:25], v[188:189] op_sel_hi:[1,0]
	v_pk_mul_f32 v[26:27], v[26:27], v[188:189] op_sel_hi:[1,0]
	v_pk_mul_f32 v[28:29], v[28:29], v[188:189] op_sel_hi:[1,0]
	v_pk_mul_f32 v[30:31], v[30:31], v[188:189] op_sel_hi:[1,0]
	v_pk_mul_f32 v[32:33], v[32:33], v[188:189] op_sel_hi:[1,0]
	v_mul_f32_e32 v165, v188, v165
.Lc1_nr:
	v_mov_b32_e32 v166, v186
	v_sub_f32_e32 v184, v208, v182
	v_pk_fma_f32 v[34:35], v[34:35], v[190:191], v[184:185] op_sel_hi:[1,0,0]
	v_pk_fma_f32 v[36:37], v[36:37], v[190:191], v[184:185] op_sel_hi:[1,0,0]
	v_pk_fma_f32 v[38:39], v[38:39], v[190:191], v[184:185] op_sel_hi:[1,0,0]
	v_pk_fma_f32 v[40:41], v[40:41], v[190:191], v[184:185] op_sel_hi:[1,0,0]
	v_exp_f32_e32 v34, v34
	v_exp_f32_e32 v35, v35
	v_exp_f32_e32 v36, v36
	v_exp_f32_e32 v37, v37
	v_exp_f32_e32 v38, v38
	v_exp_f32_e32 v39, v39
	v_exp_f32_e32 v40, v40
	v_exp_f32_e32 v41, v41
	v_pk_add_f32 v[192:193], v[34:35], v[36:37]
	v_pk_add_f32 v[192:193], v[192:193], v[38:39]
	v_pk_add_f32 v[192:193], v[192:193], v[40:41]
	v_cvt_pk_bf16_f32 v168, v34, v35
	v_cvt_pk_bf16_f32 v169, v36, v37
	v_cvt_pk_bf16_f32 v170, v38, v39
	v_cvt_pk_bf16_f32 v171, v40, v41
	v_pk_fma_f32 v[42:43], v[42:43], v[190:191], v[184:185] op_sel_hi:[1,0,0]
	v_pk_fma_f32 v[44:45], v[44:45], v[190:191], v[184:185] op_sel_hi:[1,0,0]
	v_pk_fma_f32 v[46:47], v[46:47], v[190:191], v[184:185] op_sel_hi:[1,0,0]
	v_pk_fma_f32 v[48:49], v[48:49], v[190:191], v[184:185] op_sel_hi:[1,0,0]
	s_cmp_lg_u32 s24, 0
	s_cbranch_scc1 .Lc1_w8
	s_waitcnt vmcnt(0)
	s_branch .Lc1_pv

.Lc1_pv:
	v_mfma_f32_32x32x16_bf16 v[2:17], v[98:101], v[168:171], v[2:17]
	v_mfma_f32_32x32x16_bf16 v[18:33], v[114:117], v[168:171], v[18:33]
	v_exp_f32_e32 v42, v42
	v_exp_f32_e32 v43, v43
	v_exp_f32_e32 v44, v44
	v_exp_f32_e32 v45, v45
	v_exp_f32_e32 v46, v46
	v_exp_f32_e32 v47, v47
	v_exp_f32_e32 v48, v48
	v_exp_f32_e32 v49, v49
	v_pk_add_f32 v[192:193], v[192:193], v[42:43]
	v_pk_add_f32 v[192:193], v[192:193], v[44:45]
	v_pk_add_f32 v[192:193], v[192:193], v[46:47]
	v_pk_add_f32 v[192:193], v[192:193], v[48:49]
	v_cvt_pk_bf16_f32 v172, v42, v43
	v_cvt_pk_bf16_f32 v173, v44, v45
	v_cvt_pk_bf16_f32 v174, v46, v47
	v_cvt_pk_bf16_f32 v175, v48, v49
	v_pk_fma_f32 v[50:51], v[50:51], v[190:191], v[184:185] op_sel_hi:[1,0,0]
	v_pk_fma_f32 v[52:53], v[52:53], v[190:191], v[184:185] op_sel_hi:[1,0,0]
	v_pk_fma_f32 v[54:55], v[54:55], v[190:191], v[184:185] op_sel_hi:[1,0,0]
	v_pk_fma_f32 v[56:57], v[56:57], v[190:191], v[184:185] op_sel_hi:[1,0,0]
	v_mfma_f32_32x32x16_bf16 v[2:17], v[102:105], v[172:175], v[2:17]
	v_mfma_f32_32x32x16_bf16 v[18:33], v[118:121], v[172:175], v[18:33]
	v_exp_f32_e32 v50, v50
	v_exp_f32_e32 v51, v51
	v_exp_f32_e32 v52, v52
	v_exp_f32_e32 v53, v53
	v_exp_f32_e32 v54, v54
	v_exp_f32_e32 v55, v55
	v_exp_f32_e32 v56, v56
	v_exp_f32_e32 v57, v57
	v_pk_add_f32 v[192:193], v[192:193], v[50:51]
	v_pk_add_f32 v[192:193], v[192:193], v[52:53]
	v_pk_add_f32 v[192:193], v[192:193], v[54:55]
	v_pk_add_f32 v[192:193], v[192:193], v[56:57]
	v_cvt_pk_bf16_f32 v168, v50, v51
	v_cvt_pk_bf16_f32 v169, v52, v53
	v_cvt_pk_bf16_f32 v170, v54, v55
	v_cvt_pk_bf16_f32 v171, v56, v57
	v_pk_fma_f32 v[58:59], v[58:59], v[190:191], v[184:185] op_sel_hi:[1,0,0]
	v_pk_fma_f32 v[60:61], v[60:61], v[190:191], v[184:185] op_sel_hi:[1,0,0]
	v_pk_fma_f32 v[62:63], v[62:63], v[190:191], v[184:185] op_sel_hi:[1,0,0]
	v_pk_fma_f32 v[64:65], v[64:65], v[190:191], v[184:185] op_sel_hi:[1,0,0]
	v_mfma_f32_32x32x16_bf16 v[2:17], v[106:109], v[168:171], v[2:17]
	v_mfma_f32_32x32x16_bf16 v[18:33], v[122:125], v[168:171], v[18:33]
	v_exp_f32_e32 v58, v58
	v_exp_f32_e32 v59, v59
	v_exp_f32_e32 v60, v60
	v_exp_f32_e32 v61, v61
	v_exp_f32_e32 v62, v62
	v_exp_f32_e32 v63, v63
	v_exp_f32_e32 v64, v64
	v_exp_f32_e32 v65, v65
	v_pk_add_f32 v[192:193], v[192:193], v[58:59]
	v_pk_add_f32 v[192:193], v[192:193], v[60:61]
	v_pk_add_f32 v[192:193], v[192:193], v[62:63]
	v_pk_add_f32 v[192:193], v[192:193], v[64:65]
	v_cvt_pk_bf16_f32 v172, v58, v59
	v_cvt_pk_bf16_f32 v173, v60, v61
	v_cvt_pk_bf16_f32 v174, v62, v63
	v_cvt_pk_bf16_f32 v175, v64, v65
	s_nop 1
	v_mfma_f32_32x32x16_bf16 v[2:17], v[110:113], v[172:175], v[2:17]
	v_mfma_f32_32x32x16_bf16 v[18:33], v[126:129], v[172:175], v[18:33]
	v_add_f32_e32 v187, v192, v193
	v_add_f32_e32 v165, v165, v187
	s_add_u32 s12, s12, 0x2000
	s_addc_u32 s13, s13, 0
	s_add_i32 s11, s11, 64
	v_add_u32_e32 v164, 0xfffffc00, v164
	s_add_u32 s18, s18, 0x2000
	s_addc_u32 s19, s19, 0
	s_cmp_lg_u32 s24, 0
	s_cbranch_scc1 .Lc1_loop
	s_cmp_eq_u32 s16, s12
	s_cbranch_scc0 .LBB0_1279
	s_nop 7
	s_nop 7
	v_mov_b64_e32 v[34:35], v[2:3]
	v_mov_b64_e32 v[36:37], v[4:5]
	v_mov_b64_e32 v[38:39], v[6:7]
	v_mov_b64_e32 v[40:41], v[8:9]
	v_mov_b64_e32 v[42:43], v[10:11]
	v_mov_b64_e32 v[44:45], v[12:13]
	v_mov_b64_e32 v[46:47], v[14:15]
	v_mov_b64_e32 v[48:49], v[16:17]
	v_mov_b64_e32 v[50:51], v[18:19]
	v_mov_b64_e32 v[52:53], v[20:21]
	v_mov_b64_e32 v[54:55], v[22:23]
	v_mov_b64_e32 v[56:57], v[24:25]
	v_mov_b64_e32 v[58:59], v[26:27]
	v_mov_b64_e32 v[60:61], v[28:29]
	v_mov_b64_e32 v[62:63], v[30:31]
	v_mov_b64_e32 v[64:65], v[32:33]
	v_mov_b32_e32 v167, v166
	v_mov_b32_e32 v168, v165
	s_branch .LBB0_1290
